# rw_chunk_prep head: LoRA tiles, per-channel params and previous-token rows loaded in one burst, on top of token-load hoist
# speedup vs baseline: 1.0187x; 1.0010x over previous
; #define LAS __attribute__((address_space(3)))
; __device__ __forceinline__ f32x4 bf4(v2u u) { return (f32x4){bflo(u.x), bfhi(u.x), bflo(u.y), bfhi(u.y)}; }
; #define MFMA32(a, b, c) __builtin_amdgcn_mfma_f32_16x16x32_bf16(a, b, c, 0, 0, 0)
; __device__ __forceinline__ void rw_chunk_prep(const Args& a, int head, int tc0, const LAS bf16* TDr, const LAS bf16* DAr, LAS unsigned char* lw_, int lane) {
;     ...
;     {   bf16x8 atd[2], ada[2];
; #pragma unroll
;         for (int kk = 0; kk < 2; ++kk) { atd[kk] = *(const LAS bf16x8*)(TDr + j * 64 + kk * 32 + kg * 8); ada[kk] = *(const LAS bf16x8*)(DAr + j * 64 + kk * 32 + kg * 8); }
; #pragma unroll
;         for (int cb = 0; cb < 4; ++cb) { accw[cb] = (f32x4){0.f, 0.f, 0.f, 0.f}; acca[cb] = (f32x4){0.f, 0.f, 0.f, 0.f};
; #pragma unroll
;             for (int kk = 0; kk < 2; ++kk) { const bf16x8 bw = *(const bf16x8*)(W2t + (size_t)(cbase + cb) * 64 + kk * 32 + kg * 8), ba = *(const bf16x8*)(A2t + (size_t)(cbase + cb) * 64 + kk * 32 + kg * 8);
;                 accw[cb] = MFMA32(atd[kk], bw, accw[cb]); acca[cb] = MFMA32(ada[kk], ba, acca[cb]); } }
;     }
;     const f32x4 w0 = ld4(a.in[9] + cbase), a0 = ld4(a.in[11] + cbase), kkw = ld4(a.in[13] + cbase), kaw = ld4(a.in[14] + cbase), rkw = ld4(a.in[15] + cbase);
;     const f32x4 mur = ld4(a.in[4] + cbase), muk = ld4(a.in[5] + cbase), muv = ld4(a.in[6] + cbase);
;     float* RK = (float*)(ws + WS_RK);
;     f32x4 rr[4], km[4], av[4], bv[4], lw[4], vv[4];
;     {   const int tt0 = tc0 + 4 * rg; const f32x4 zero = {0.f, 0.f, 0.f, 0.f};
;         f32x4 pr = tt0 > 0 ? bf4(*(const v2u*)(ZA + (size_t)(tt0 - 1) * 3072 + cbase)) : zero;
;         f32x4 pk = tt0 > 0 ? bf4(*(const v2u*)(ZA + (size_t)(tt0 - 1) * 3072 + 1024 + cbase)) : zero;
;         f32x4 pv = tt0 > 0 ? bf4(*(const v2u*)(ZA + (size_t)(tt0 - 1) * 3072 + 2048 + cbase)) : zero;
.LBB0_329:
	s_lshr_b32 s0, s59, 1
	s_add_i32 s0, s0, s34
	s_and_b32 s2, s58, 16
	v_lshl_add_u32 v208, s2, 7, v155
	v_lshl_or_b32 v66, s0, 6, v154
	ds_read_b128 v[246:249], v208
	ds_read_b128 v[250:253], v208 offset:4096
	ds_read_b128 v[204:207], v208 offset:64
	ds_read_b128 v[132:135], v208 offset:4160
	v_lshlrev_b64 v[140:141], 7, v[66:67]
	v_lshl_add_u64 v[142:143], v[74:75], 0, v[140:141]
	v_lshl_add_u64 v[144:145], v[76:77], 0, v[140:141]
	global_load_dwordx4 v[4:7], v[142:143], off
	global_load_dwordx4 v[24:27], v[144:145], off
	global_load_dwordx4 v[214:217], v[142:143], off offset:64
	global_load_dwordx4 v[230:233], v[144:145], off offset:64
	global_load_dwordx4 v[8:11], v[142:143], off offset:128
	global_load_dwordx4 v[28:31], v[144:145], off offset:128
	global_load_dwordx4 v[218:221], v[142:143], off offset:192
	global_load_dwordx4 v[234:237], v[144:145], off offset:192
	global_load_dwordx4 v[12:15], v[142:143], off offset:256
	global_load_dwordx4 v[32:35], v[144:145], off offset:256
	global_load_dwordx4 v[222:225], v[142:143], off offset:320
	global_load_dwordx4 v[238:241], v[144:145], off offset:320
	global_load_dwordx4 v[16:19], v[142:143], off offset:384
	global_load_dwordx4 v[56:59], v[144:145], off offset:384
	global_load_dwordx4 v[226:229], v[142:143], off offset:448
	global_load_dwordx4 v[242:245], v[144:145], off offset:448
	v_lshlrev_b64 v[140:141], 2, v[66:67]
	v_lshl_add_u64 v[146:147], s[38:39], 0, v[140:141]
	global_load_dwordx4 v[20:23], v[146:147], off
	v_lshl_add_u64 v[146:147], s[42:43], 0, v[140:141]
	global_load_dwordx4 v[60:63], v[146:147], off
	v_lshl_add_u64 v[146:147], s[46:47], 0, v[140:141]
	global_load_dwordx4 v[36:39], v[146:147], off
	v_lshl_add_u64 v[146:147], s[48:49], 0, v[140:141]
	global_load_dwordx4 v[52:55], v[146:147], off
	v_lshl_add_u64 v[146:147], s[50:51], 0, v[140:141]
	global_load_dwordx4 v[40:43], v[146:147], off
	v_lshl_add_u64 v[146:147], s[76:77], 0, v[140:141]
	global_load_dwordx4 v[44:47], v[146:147], off
	v_lshl_add_u64 v[146:147], s[78:79], 0, v[140:141]
	global_load_dwordx4 v[48:51], v[146:147], off
	v_lshl_add_u64 v[146:147], s[80:81], 0, v[140:141]
	global_load_dwordx4 v[0:3], v[146:147], off
	v_lshlrev_b32_e32 v66, 1, v66
	s_or_b32 s60, s2, s57
	v_add_u32_e32 v106, s60, v157
	v_add_u32_e32 v96, -1, v106
	v_mov_b64_e32 v[148:149], s[72:73]
	v_mad_u64_u32 v[148:149], s[26:27], v96, s44, v[148:149]
	v_lshl_add_u64 v[148:149], v[148:149], 0, v[66:67]
	v_add_co_u32_e32 v148, vcc, 0x800, v148
	s_nop 1
	v_addc_co_u32_e32 v149, vcc, 0, v149, vcc
	v_cmp_lt_i32_e32 vcc, 0, v106
	v_mov_b32_e32 v100, 0
	v_mov_b32_e32 v101, 0
	v_mov_b32_e32 v104, 0
	v_mov_b32_e32 v105, 0
	v_mov_b32_e32 v150, 0
	v_mov_b32_e32 v151, 0
	s_and_saveexec_b64 s[2:3], vcc
	global_load_dwordx2 v[100:101], v[148:149], off offset:-2048
	global_load_dwordx2 v[104:105], v[148:149], off
	global_load_dwordx2 v[150:151], v[148:149], off offset:2048
	s_or_b64 exec, exec, s[2:3]
	s_waitcnt vmcnt(11) lgkmcnt(0)
	v_mfma_f32_16x16x32_bf16 v[4:7], v[246:249], v[4:7], 0
	v_mfma_f32_16x16x32_bf16 v[24:27], v[250:253], v[24:27], 0
	v_mfma_f32_16x16x32_bf16 v[8:11], v[246:249], v[8:11], 0
	v_mfma_f32_16x16x32_bf16 v[28:31], v[250:253], v[28:31], 0
	v_mfma_f32_16x16x32_bf16 v[12:15], v[246:249], v[12:15], 0
	v_mfma_f32_16x16x32_bf16 v[32:35], v[250:253], v[32:35], 0
	v_mfma_f32_16x16x32_bf16 v[16:19], v[246:249], v[16:19], 0
	v_mfma_f32_16x16x32_bf16 v[56:59], v[250:253], v[56:59], 0
	v_mfma_f32_16x16x32_bf16 v[4:7], v[204:207], v[214:217], v[4:7]
	v_mfma_f32_16x16x32_bf16 v[24:27], v[132:135], v[230:233], v[24:27]
	v_mfma_f32_16x16x32_bf16 v[8:11], v[204:207], v[218:221], v[8:11]
	v_mfma_f32_16x16x32_bf16 v[28:31], v[132:135], v[234:237], v[28:31]
	v_mfma_f32_16x16x32_bf16 v[12:15], v[204:207], v[222:225], v[12:15]
	v_mfma_f32_16x16x32_bf16 v[32:35], v[132:135], v[238:241], v[32:35]
	v_mfma_f32_16x16x32_bf16 v[16:19], v[204:207], v[226:229], v[16:19]
	v_mfma_f32_16x16x32_bf16 v[56:59], v[132:135], v[242:245], v[56:59]
	s_waitcnt vmcnt(0)
	v_lshlrev_b32_e32 v98, 16, v100
	v_and_b32_e32 v100, 0xffff0000, v100
	v_lshlrev_b32_e32 v99, 16, v101
	v_and_b32_e32 v101, 0xffff0000, v101
	v_lshlrev_b32_e32 v102, 16, v104
	v_and_b32_e32 v103, 0xffff0000, v104
	v_lshlrev_b32_e32 v104, 16, v105
	v_and_b32_e32 v105, 0xffff0000, v105
	v_lshlrev_b32_e32 v186, 16, v150
	v_and_b32_e32 v188, 0xffff0000, v150
	v_lshlrev_b32_e32 v187, 16, v151
	v_and_b32_e32 v189, 0xffff0000, v151
	v_mov_b64_e32 v[96:97], s[72:73]
	v_mad_i64_i32 v[96:97], s[2:3], v106, s44, v[96:97]
	v_lshl_add_u64 v[96:97], v[96:97], 0, v[66:67]
	global_load_dwordx2 v[108:109], v[96:97], off
	global_load_dwordx2 v[110:111], v[96:97], off offset:2048
	v_add_co_u32_e32 v96, vcc, s45, v96
	s_waitcnt vmcnt(8)
; __device__ __forceinline__ f32x4 bf4(v2u u) { return (f32x4){bflo(u.x), bfhi(u.x), bflo(u.y), bfhi(u.y)}; }
; __device__ __forceinline__ void rw_chunk_prep(const Args& a, int head, int tc0, const LAS bf16* TDr, const LAS bf16* DAr, LAS unsigned char* lw_, int lane) {
;     ...
;     {   const int tt0 = tc0 + 4 * rg; const f32x4 zero = {0.f, 0.f, 0.f, 0.f};
;         f32x4 pr = tt0 > 0 ? bf4(*(const v2u*)(ZA + (size_t)(tt0 - 1) * 3072 + cbase)) : zero;
;         f32x4 pk = tt0 > 0 ? bf4(*(const v2u*)(ZA + (size_t)(tt0 - 1) * 3072 + 1024 + cbase)) : zero;
;         f32x4 pv = tt0 > 0 ? bf4(*(const v2u*)(ZA + (size_t)(tt0 - 1) * 3072 + 2048 + cbase)) : zero;
; #pragma unroll
;         for (int i = 0; i < 4; ++i) {
;             const int tt = tt0 + i;
;             const f32x4 zr = bf4(*(const v2u*)(ZA + (size_t)tt * 3072 + cbase)), zk = bf4(*(const v2u*)(ZA + (size_t)tt * 3072 + 1024 + cbase)), zv = bf4(*(const v2u*)(ZA + (size_t)tt * 3072 + 2048 + cbase));
;             const f32x4 r = zr + (pr - zr) * mur, k = zk + (pk - zk) * muk, v = zv + (pv - zv) * muv;
;             pr = zr; pk = zk; pv = zv;
;             f32x4 lwv, alr;
; #pragma unroll
;             for (int cb = 0; cb < 4; ++cb) { const float x = -(w0[cb] + accw[cb][i]); const float sp = fmaxf(x, 0.f) + __logf(1.f + __expf(-fabsf(x))); lwv[cb] = -__expf(-sp - 0.5f); alr[cb] = __builtin_amdgcn_rcpf(1.f + __expf(-(a0[cb] + acca[cb][i]))); }
;             const f32x4 kkr = k * kkw, kmod = k * (1.f + (alr - 1.f) * kaw);
;             float ssq = (kkr.x * kkr.x + kkr.y * kkr.y) + (kkr.z * kkr.z + kkr.w * kkr.w);
;             const f32x4 rkk = r * kmod * rkw; float rkp = (rkk.x + rkk.y) + (rkk.z + rkk.w);
;             ssq = row16_sum(ssq); rkp = row16_sum(rkp);
;             const float inv = __builtin_amdgcn_rsqf(fmaxf(ssq, 1e-24f));
;             const f32x4 kk = kkr * inv;
;             rr[i] = r; km[i] = kmod; av[i] = -kk; bv[i] = kk * alr; lw[i] = lwv; vv[i] = v;
;             if (j == 0) RK[(size_t)tt * 16 + head] = rkp;
	v_add_f32_e32 v107, v24, v60
	v_addc_co_u32_e32 v97, vcc, 0, v97, vcc
	global_load_dwordx2 v[96:97], v[96:97], off
	v_mov_b32_e32 v230, s45
	v_mov_b32_e32 v231, 0
	v_or_b32_e32 v224, 1, v106
	v_mov_b64_e32 v[226:227], s[72:73]
	v_mad_i64_i32 v[226:227], s[2:3], v224, s44, v[226:227]
	v_lshl_add_u64 v[226:227], v[226:227], 0, v[66:67]
	v_lshl_add_u64 v[228:229], v[226:227], 0, v[230:231]
	global_load_dwordx2 v[206:207], v[226:227], off
	global_load_dwordx2 v[208:209], v[226:227], off offset:2048
	global_load_dwordx2 v[210:211], v[228:229], off
	v_or_b32_e32 v224, 2, v106
	v_mov_b64_e32 v[232:233], s[72:73]
	v_mad_i64_i32 v[232:233], s[2:3], v224, s44, v[232:233]
	v_lshl_add_u64 v[232:233], v[232:233], 0, v[66:67]
	v_lshl_add_u64 v[234:235], v[232:233], 0, v[230:231]
	global_load_dwordx2 v[212:213], v[232:233], off
	global_load_dwordx2 v[214:215], v[232:233], off offset:2048
	global_load_dwordx2 v[216:217], v[234:235], off
	v_or_b32_e32 v224, 3, v106
	v_mov_b64_e32 v[238:239], s[72:73]
	v_mad_i64_i32 v[238:239], s[2:3], v224, s44, v[238:239]
	v_lshl_add_u64 v[238:239], v[238:239], 0, v[66:67]
	v_lshl_add_u64 v[240:241], v[238:239], 0, v[230:231]
	global_load_dwordx2 v[218:219], v[238:239], off
	global_load_dwordx2 v[220:221], v[238:239], off offset:2048
	global_load_dwordx2 v[222:223], v[240:241], off
	v_add_f32_e32 v28, v28, v61
	v_add_f32_e32 v32, v32, v62
	v_add_f32_e32 v56, v56, v63
	v_mul_f32_e32 v107, 0xbfb8aa3b, v107
	v_mul_f32_e32 v28, 0xbfb8aa3b, v28
	v_mul_f32_e32 v32, 0xbfb8aa3b, v32
	v_mul_f32_e32 v56, 0xbfb8aa3b, v56
	v_exp_f32_e32 v107, v107
	v_exp_f32_e32 v28, v28
	v_exp_f32_e32 v32, v32
	v_exp_f32_e32 v56, v56
	v_add_f32_e32 v107, 1.0, v107
	v_add_f32_e32 v28, 1.0, v28
	v_add_f32_e32 v32, 1.0, v32
	v_add_f32_e32 v56, 1.0, v56
	v_rcp_f32_e32 v112, v107
	v_rcp_f32_e32 v114, v32
	v_rcp_f32_e32 v115, v56
	v_rcp_f32_e32 v113, v28
	s_lshl_b64 s[2:3], s[0:1], 2
	v_mov_b32_e32 v190, v67
	v_pk_add_f32 v[116:117], v[114:115], -1.0 op_sel_hi:[1,0]
	v_pk_add_f32 v[118:119], v[112:113], -1.0 op_sel_hi:[1,0]
	s_waitcnt vmcnt(16)
	v_pk_fma_f32 v[130:131], v[54:55], v[116:117], 1.0 op_sel_hi:[1,1,0]
	v_pk_fma_f32 v[128:129], v[52:53], v[118:119], 1.0 op_sel_hi:[1,1,0]
	v_mov_b32_e32 v24, v67
	s_add_u32 s26, s35, s2
	s_addc_u32 s27, s36, s3
	s_waitcnt vmcnt(11)
	v_lshlrev_b32_e32 v122, 16, v108
	v_and_b32_e32 v123, 0xffff0000, v108
	v_lshlrev_b32_e32 v124, 16, v109
	s_waitcnt vmcnt(10)
	v_lshlrev_b32_e32 v120, 16, v110
	v_and_b32_e32 v121, 0xffff0000, v110
	v_lshlrev_b32_e32 v126, 16, v111
	v_and_b32_e32 v127, 0xffff0000, v111
	v_and_b32_e32 v125, 0xffff0000, v109
	v_sub_f32_e32 v109, v100, v123
	v_sub_f32_e32 v108, v98, v122
	v_sub_f32_e32 v100, v99, v124
	v_sub_f32_e32 v99, v105, v127
	v_sub_f32_e32 v98, v104, v126
	v_sub_f32_e32 v103, v103, v121
	v_sub_f32_e32 v102, v102, v120
	v_sub_f32_e32 v101, v101, v125
	v_pk_fma_f32 v[102:103], v[48:49], v[102:103], v[120:121]
	v_pk_fma_f32 v[98:99], v[50:51], v[98:99], v[126:127]
	v_pk_fma_f32 v[110:111], v[46:47], v[100:101], v[124:125]
	v_pk_fma_f32 v[108:109], v[44:45], v[108:109], v[122:123]
	v_pk_mul_f32 v[118:119], v[38:39], v[98:99]
	v_pk_mul_f32 v[116:117], v[36:37], v[102:103]
	v_pk_mul_f32 v[100:101], v[130:131], v[98:99]
	v_pk_mul_f32 v[102:103], v[128:129], v[102:103]
	v_pk_mul_f32 v[98:99], v[118:119], v[118:119]
	v_pk_mul_f32 v[104:105], v[116:117], v[116:117]
	v_pk_mul_f32 v[128:129], v[108:109], v[102:103]
	v_pk_mul_f32 v[130:131], v[110:111], v[100:101]
	v_pk_mov_b32 v[132:133], v[104:105], v[98:99] op_sel:[1,0]
	v_mov_b32_e32 v105, v99
	v_pk_mul_f32 v[98:99], v[42:43], v[130:131]
	v_pk_mul_f32 v[128:129], v[40:41], v[128:129]
	v_pk_add_f32 v[104:105], v[132:133], v[104:105]
	v_add_f32_e32 v28, v128, v129
	v_add_f32_e32 v32, v98, v99
	v_add_f32_e32 v56, v104, v105
	v_add_f32_e32 v28, v28, v32
	s_nop 0
	v_add_f32_dpp v32, v56, v56 quad_perm:[1,0,3,2] row_mask:0xf bank_mask:0xf bound_ctrl:1
	v_add_f32_dpp v28, v28, v28 quad_perm:[1,0,3,2] row_mask:0xf bank_mask:0xf bound_ctrl:1
	s_nop 0
	v_add_f32_dpp v32, v32, v32 quad_perm:[2,3,0,1] row_mask:0xf bank_mask:0xf bound_ctrl:1
	v_add_f32_dpp v28, v28, v28 quad_perm:[2,3,0,1] row_mask:0xf bank_mask:0xf bound_ctrl:1
	s_nop 0
	v_add_f32_dpp v191, v32, v32 row_half_mirror row_mask:0xf bank_mask:0xf bound_ctrl:1
	v_add_f32_dpp v28, v28, v28 row_half_mirror row_mask:0xf bank_mask:0xf bound_ctrl:1
	s_nop 0
	v_mov_b32_dpp v190, v191 row_mirror row_mask:0xf bank_mask:0xf
	v_mov_b32_dpp v24, v28 row_mirror row_mask:0xf bank_mask:0xf
	s_and_saveexec_b64 s[2:3], s[24:25]
	s_cbranch_execz .LBB0_337
	v_ashrrev_i32_e32 v107, 31, v106
	v_lshlrev_b64 v[98:99], 6, v[106:107]
	v_lshl_add_u64 v[98:99], s[26:27], 0, v[98:99]
	v_add_f32_e32 v24, v28, v24
	global_store_dword v[98:99], v24, off
